# attention tile loop: blocks laid out for fallthrough (one taken branch per two tiles instead of six), single DMA guard branch
# baseline (speedup 1.0000x reference)
; template <bool SHIFT> DI void phase_attn2(const Params& p, const Grp& G, int layer, LAS unsigned char* lds, int tid, int wave, int lane, int vcu, bool dry) {
;     ...
;         { unsigned dfl = doff0; asm volatile("" : "+v"(dfl)); AT2_DMA(0, 0); }
;     ...
;         for (int t = 0; t < NT; ++t) {
;             unsigned dfl = doff0; asm volatile("" : "+v"(dfl));
;             if (t + 1 < NT) AT2_DMA(t + 1, (t + 1) & 1);
.Lat2_top_O:
	ds_read_b128 v[128:131], v217 offset:32768
	ds_read_b128 v[160:163], v236 offset:32768
	ds_read_b128 v[166:169], v237 offset:32768
	ds_read_b128 v[170:173], v238 offset:32768
	s_add_i32 s38, s38, 1
	s_add_i32 s39, s8, 0x8000
	s_cmp_lt_u32 s38, s45
	s_cbranch_scc0 .Lat2_body_O
	s_and_b32 s0, s39, 0x8000
	s_add_u32 s100, s30, s80
	s_addc_u32 s101, s31, s81
	s_add_i32 s0, s33, s0
	s_mov_b32 m0, s0
	s_nop 0
	global_load_lds_dwordx4 v219, s[100:101]
	s_add_i32 m0, s0, 0x4000
	s_nop 0
	global_load_lds_dwordx4 v219, s[30:31]
	s_add_i32 m0, s0, 0x400
	s_nop 0
	global_load_lds_dwordx4 v252, s[100:101]
	s_add_i32 m0, s0, 0x4400
	s_nop 0
	global_load_lds_dwordx4 v252, s[30:31]

; template <bool SHIFT> DI void phase_attn2(const Params& p, const Grp& G, int layer, LAS unsigned char* lds, int tid, int wave, int lane, int vcu, bool dry) {
;     ...
;         { unsigned dfl = doff0; asm volatile("" : "+v"(dfl)); AT2_DMA(0, 0); }
;     ...
;         for (int t = 0; t < NT; ++t) {
;             unsigned dfl = doff0; asm volatile("" : "+v"(dfl));
;             if (t + 1 < NT) AT2_DMA(t + 1, (t + 1) & 1);
.LBB0_379:
	ds_read_b128 v[128:131], v217
	ds_read_b128 v[160:163], v236
	ds_read_b128 v[166:169], v237
	ds_read_b128 v[170:173], v238
	s_add_i32 s38, s38, 1
	s_add_i32 s39, s8, 0x8000
	s_cmp_lt_u32 s38, s45
	s_cbranch_scc0 .LBB0_378
	s_and_b32 s0, s39, 0x8000
	s_add_u32 s100, s30, s80
	s_addc_u32 s101, s31, s81
	s_add_i32 s0, s33, s0
	s_mov_b32 m0, s0
	s_nop 0
	global_load_lds_dwordx4 v219, s[100:101]
	s_add_i32 m0, s0, 0x4000
	s_nop 0
	global_load_lds_dwordx4 v219, s[30:31]
	s_add_i32 m0, s0, 0x400
	s_nop 0
	global_load_lds_dwordx4 v252, s[100:101]
	s_add_i32 m0, s0, 0x4400
	s_nop 0
	global_load_lds_dwordx4 v252, s[30:31]
	s_branch .LBB0_378
